# strategy 7: v_permlane32_swap instead of ds_bpermute round trip for the attention row-max exchange
# baseline (speedup 1.0000x reference)
; #define LAS __attribute__((address_space(3)))
; __device__ __forceinline__ void attn_wave_unit(LAS unsigned char* wl, const bf16* __restrict__ Q, const bf16* __restrict__ Kb, const bf16* __restrict__ V, const float* ssq_x, const float* ssq_qk, ...
;     ...
;         f32x16 s, sb;
; #pragma unroll
;         for (int e = 0; e < 16; ++e) { s[e] = 0.f; sb[e] = 0.f; }
; #pragma unroll
;         for (int ks = 0; ks < 8; ks += 2) {
;             const bf16x8 k0 = *(const LAS bf16x8*)(wl + kfbase + 32 * ks), k1 = *(const LAS bf16x8*)(wl + kfbase + 32 * ks + 32);
;             s = __builtin_amdgcn_mfma_f32_32x32x16_bf16(k0, qf[ks], s, 0, 0, 0); sb = __builtin_amdgcn_mfma_f32_32x32x16_bf16(k1, qf[ks + 1], sb, 0, 0, 0); }
;         s = s + sb;
;         float mt = -INFINITY;
; #pragma unroll
;         for (int g4 = 0; g4 < 4; ++g4) { const f32x4 ck4 = *(const LAS f32x4*)(ckl + 32 * t + 8 * g4 + 4 * hh);
; #pragma unroll
;             for (int j = 0; j < 4; ++j) { const int rr = 4 * g4 + j; const int ka = kb + 8 * g4 + 4 * hh + j; const int df = ka - qa;
;                 const bool ok = ((unsigned)ka < (unsigned)L) & ((unsigned)(df + 64) <= 128u);
;                 const float v = s[rr] * (cq * ck4[j]); const float sc = ok ? v : -INFINITY; s[rr] = sc; mt = fmaxf(mt, sc); } }
;         mt = fmaxf(mt, __shfl_xor(mt, 32));
.LBB0_523:
	s_waitcnt lgkmcnt(0)
	v_add_u32_e32 v247, v231, v230
	ds_read_b128 v[64:67], v247 offset:10240
	ds_read_b128 v[80:83], v247 offset:10272
	ds_read_b128 v[248:251], v247 offset:10304
	ds_read_b128 v[196:199], v247 offset:10336
	s_mov_b32 s41, 0xff800000
	s_waitcnt lgkmcnt(0)
	v_mfma_f32_32x32x16_bf16 v[64:79], v[64:67], v[98:101], 0
	v_mfma_f32_32x32x16_bf16 v[80:95], v[80:83], v[102:105], 0
	v_mfma_f32_32x32x16_bf16 v[64:79], v[248:251], v[106:109], v[64:79]
	v_mfma_f32_32x32x16_bf16 v[80:95], v[196:199], v[110:113], v[80:95]
	ds_read_b128 v[196:199], v247 offset:10368
	ds_read_b128 v[248:251], v247 offset:10400
	s_waitcnt lgkmcnt(0)
	v_mfma_f32_32x32x16_bf16 v[64:79], v[196:199], v[114:117], v[64:79]
	v_mfma_f32_32x32x16_bf16 v[80:95], v[248:251], v[118:121], v[80:95]
	ds_read_b128 v[196:199], v247 offset:10432
	ds_read_b128 v[248:251], v247 offset:10464
	s_waitcnt lgkmcnt(0)
	v_mfma_f32_32x32x16_bf16 v[64:79], v[196:199], v[122:125], v[64:79]
	v_mfma_f32_32x32x16_bf16 v[80:95], v[248:251], v[126:129], v[80:95]
	s_nop 11
	v_pk_add_f32 v[82:83], v[66:67], v[82:83]
	v_pk_add_f32 v[80:81], v[64:65], v[80:81]
	ds_read_b128 v[64:67], v244
	v_pk_add_f32 v[72:73], v[72:73], v[88:89]
	v_add_u32_e32 v88, s40, v243
	v_pk_add_f32 v[84:85], v[68:69], v[84:85]
	v_subrev_u32_e32 v68, 64, v88
	v_cmp_gt_u32_e32 vcc, s93, v68
	v_sub_u32_e32 v68, v203, v227
	v_add_u32_e32 v89, s40, v68
	v_pk_add_f32 v[86:87], v[70:71], v[86:87]
	v_cmp_gt_u32_e64 s[60:61], s4, v89
	ds_read_b128 v[68:71], v244 offset:32
	s_waitcnt lgkmcnt(0)
	v_mul_f32_e32 v64, v242, v64
	v_mul_f32_e32 v64, v80, v64
	s_and_b64 vcc, vcc, s[60:61]
	v_cndmask_b32_e32 v80, v222, v64, vcc
	v_subrev_u32_e32 v64, 63, v88
	v_cmp_gt_u32_e32 vcc, s93, v64
	v_add_u32_e32 v64, 1, v89
	v_cmp_gt_u32_e64 s[60:61], s4, v64
	v_mul_f32_e32 v64, v242, v65
	v_mul_f32_e32 v64, v81, v64
	s_and_b64 vcc, vcc, s[60:61]
	v_subrev_u32_e32 v65, 62, v88
	v_cndmask_b32_e32 v81, v222, v64, vcc
	v_cmp_gt_u32_e32 vcc, s93, v65
	v_add_u32_e32 v65, 2, v89
	v_cmp_gt_u32_e64 s[60:61], s4, v65
	v_mul_f32_e32 v65, v242, v66
	v_mul_f32_e32 v65, v82, v65
	s_and_b64 vcc, vcc, s[60:61]
	v_cndmask_b32_e32 v82, v222, v65, vcc
	v_subrev_u32_e32 v65, 61, v88
	v_cmp_gt_u32_e32 vcc, s93, v65
	v_add_u32_e32 v65, 3, v89
	v_cmp_gt_u32_e64 s[60:61], s4, v65
	v_mul_f32_e32 v65, v242, v67
	v_mul_f32_e32 v65, v83, v65
	s_and_b64 vcc, vcc, s[60:61]
	v_cndmask_b32_e32 v83, v222, v65, vcc
	v_subrev_u32_e32 v65, 56, v88
	v_cmp_gt_u32_e32 vcc, s93, v65
	v_add_u32_e32 v65, 8, v89
	v_cmp_gt_u32_e64 s[60:61], s4, v65
	v_mul_f32_e32 v65, v242, v68
	v_mul_f32_e32 v65, v84, v65
	s_and_b64 vcc, vcc, s[60:61]
	v_cndmask_b32_e32 v84, v222, v65, vcc
	v_subrev_u32_e32 v65, 55, v88
	v_cmp_gt_u32_e32 vcc, s93, v65
	v_add_u32_e32 v65, 9, v89
	v_cmp_gt_u32_e64 s[60:61], s4, v65
	v_mul_f32_e32 v65, v242, v69
	v_mul_f32_e32 v65, v85, v65
	s_and_b64 vcc, vcc, s[60:61]
	v_cndmask_b32_e32 v85, v222, v65, vcc
	v_subrev_u32_e32 v65, 54, v88
	v_cmp_gt_u32_e32 vcc, s93, v65
	v_add_u32_e32 v65, 10, v89
	v_cmp_gt_u32_e64 s[60:61], s4, v65
	v_mul_f32_e32 v65, v242, v70
	v_mul_f32_e32 v65, v86, v65
	s_and_b64 vcc, vcc, s[60:61]
	v_cndmask_b32_e32 v86, v222, v65, vcc
	v_subrev_u32_e32 v65, 53, v88
	v_cmp_gt_u32_e32 vcc, s93, v65
	v_add_u32_e32 v65, 11, v89
	v_max3_f32 v64, v80, s41, v81
	v_cmp_gt_u32_e64 s[60:61], s4, v65
	v_mul_f32_e32 v65, v242, v71
	v_max3_f32 v64, v64, v82, v83
	v_mul_f32_e32 v65, v87, v65
	s_and_b64 vcc, vcc, s[60:61]
	v_max3_f32 v64, v64, v84, v85
	v_cndmask_b32_e32 v87, v222, v65, vcc
	v_pk_add_f32 v[74:75], v[74:75], v[90:91]
	v_max3_f32 v90, v64, v86, v87
	ds_read_b128 v[64:67], v244 offset:64
	v_subrev_u32_e32 v68, 48, v88
	v_cmp_gt_u32_e32 vcc, s93, v68
	v_add_u32_e32 v68, 16, v89
	v_cmp_gt_u32_e64 s[60:61], s4, v68
	ds_read_b128 v[68:71], v244 offset:96
	s_waitcnt lgkmcnt(0)
	v_mul_f32_e32 v64, v242, v64
	v_mul_f32_e32 v64, v72, v64
	s_and_b64 vcc, vcc, s[60:61]
	v_cndmask_b32_e32 v72, v222, v64, vcc
	v_subrev_u32_e32 v64, 47, v88
	v_cmp_gt_u32_e32 vcc, s93, v64
	v_add_u32_e32 v64, 17, v89
	v_cmp_gt_u32_e64 s[60:61], s4, v64
	v_mul_f32_e32 v64, v242, v65
	v_mul_f32_e32 v64, v73, v64
	s_and_b64 vcc, vcc, s[60:61]
	v_subrev_u32_e32 v65, 46, v88
	v_cndmask_b32_e32 v73, v222, v64, vcc
	v_cmp_gt_u32_e32 vcc, s93, v65
	v_add_u32_e32 v65, 18, v89
	v_cmp_gt_u32_e64 s[60:61], s4, v65
	v_mul_f32_e32 v65, v242, v66
	v_mul_f32_e32 v65, v74, v65
	s_and_b64 vcc, vcc, s[60:61]
	v_cndmask_b32_e32 v66, v222, v65, vcc
	v_subrev_u32_e32 v65, 45, v88
	v_cmp_gt_u32_e32 vcc, s93, v65
	v_add_u32_e32 v65, 19, v89
	v_cmp_gt_u32_e64 s[60:61], s4, v65
	v_mul_f32_e32 v65, v242, v67
	v_mul_f32_e32 v65, v75, v65
	s_and_b64 vcc, vcc, s[60:61]
	v_cndmask_b32_e32 v67, v222, v65, vcc
	v_subrev_u32_e32 v65, 40, v88
	v_cmp_gt_u32_e32 vcc, s93, v65
	v_add_u32_e32 v65, 24, v89
	v_pk_add_f32 v[76:77], v[76:77], v[92:93]
	v_cmp_gt_u32_e64 s[60:61], s4, v65
	v_mul_f32_e32 v65, v242, v68
	v_mul_f32_e32 v65, v76, v65
	s_and_b64 vcc, vcc, s[60:61]
	v_cndmask_b32_e32 v68, v222, v65, vcc
	v_subrev_u32_e32 v65, 39, v88
	v_cmp_gt_u32_e32 vcc, s93, v65
	v_add_u32_e32 v65, 25, v89
	v_cmp_gt_u32_e64 s[60:61], s4, v65
	v_mul_f32_e32 v65, v242, v69
	v_mul_f32_e32 v65, v77, v65
	s_and_b64 vcc, vcc, s[60:61]
	v_cndmask_b32_e32 v69, v222, v65, vcc
	v_subrev_u32_e32 v65, 38, v88
	v_cmp_gt_u32_e32 vcc, s93, v65
	v_add_u32_e32 v65, 26, v89
	v_pk_add_f32 v[78:79], v[78:79], v[94:95]
	v_cmp_gt_u32_e64 s[60:61], s4, v65
	v_mul_f32_e32 v65, v242, v70
	v_mul_f32_e32 v65, v78, v65
	s_and_b64 vcc, vcc, s[60:61]
	v_cndmask_b32_e32 v70, v222, v65, vcc
	v_subrev_u32_e32 v65, 37, v88
	v_cmp_gt_u32_e32 vcc, s93, v65
	v_add_u32_e32 v65, 27, v89
	v_max3_f32 v64, v90, v72, v73
	v_cmp_gt_u32_e64 s[60:61], s4, v65
	v_mul_f32_e32 v65, v242, v71
	v_max3_f32 v64, v64, v66, v67
	v_mul_f32_e32 v65, v79, v65
	s_and_b64 vcc, vcc, s[60:61]
	v_max3_f32 v64, v64, v68, v69
	v_cndmask_b32_e32 v71, v222, v65, vcc
	v_max3_f32 v64, v64, v70, v71
	s_add_i32 s40, s40, 32
	v_mov_b32_e32 v65, v64
	s_cmpk_eq_i32 s40, 0xa0
	v_add_u32_e32 v244, 0x80, v244
	s_nop 1
	v_permlane32_swap_b32_e32 v65, v64
	s_waitcnt lgkmcnt(0)
; __device__ __forceinline__ unsigned cvt_pk_bf16(float lo, float hi) { unsigned r; asm volatile("v_cvt_pk_bf16_f32 %0, %1, %2" : "=v"(r) : "v"(lo), "v"(hi)); return r; }
; #define LAS __attribute__((address_space(3)))
; __device__ __forceinline__ void attn_wave_unit(LAS unsigned char* wl, const bf16* __restrict__ Q, const bf16* __restrict__ Kb, const bf16* __restrict__ V, const float* ssq_x, const float* ssq_qk, ...
;     ...
;         mt = fmaxf(mt, __shfl_xor(mt, 32));
;         const float mn = fmaxf(m_run, mt); const float alpha = __builtin_amdgcn_exp2f(m_run - mn); m_run = mn;
;         float ps = 0.f;
; #pragma unroll
;         for (int e = 0; e < 16; ++e) { const float pe = __builtin_amdgcn_exp2f(s[e] - mn); s[e] = pe; ps += pe; }
;         l_run = l_run * alpha + ps;
; #pragma unroll
;         for (int db = 0; db < 4; ++db)
; #pragma unroll
;             for (int e = 0; e < 16; ++e) o[db][e] *= alpha;
;         bf16x8 pf[2];
; #pragma unroll
;         for (int s2 = 0; s2 < 2; ++s2) { u32x4 w; w.x = pg8::cvt_pk_bf16(s[8 * s2 + 0], s[8 * s2 + 1]); w.y = pg8::cvt_pk_bf16(s[8 * s2 + 2], s[8 * s2 + 3]);
;             w.z = pg8::cvt_pk_bf16(s[8 * s2 + 4], s[8 * s2 + 5]); w.w = pg8::cvt_pk_bf16(s[8 * s2 + 6], s[8 * s2 + 7]); pf[s2] = __builtin_bit_cast(bf16x8, w); }
;         bf16x8 vf[2][4];
; #pragma unroll
;         for (int s2 = 0; s2 < 2; ++s2)
; #pragma unroll
;             for (int db = 0; db < 4; ++db) {
;                 const s16x4 lo = __builtin_bit_cast(s16x4, __builtin_amdgcn_ds_read_tr16_b64_v4i16((LAS s16x4*)(wl + trbase + (16 * s2) * VPITCH + db * 64)));
;                 const s16x4 hi = __builtin_bit_cast(s16x4, __builtin_amdgcn_ds_read_tr16_b64_v4i16((LAS s16x4*)(wl + trbase + (16 * s2 + 8) * VPITCH + db * 64)));
;                 vf[s2][db] = __builtin_shufflevector(lo, hi, 0, 1, 2, 3, 4, 5, 6, 7); }
; #pragma unroll
;         for (int s2 = 0; s2 < 2; ++s2)
; #pragma unroll
;             for (int db = 0; db < 4; ++db) o[db] = __builtin_amdgcn_mfma_f32_32x32x16_bf16(vf[s2][db], pf[s2], o[db], 0, 0, 0);
	s_nop 1
	v_max3_f32 v65, v246, v64, v65
	v_sub_f32_e32 v74, v80, v65
	v_exp_f32_e32 v90, v74
	v_sub_f32_e32 v74, v81, v65
	v_exp_f32_e32 v91, v74
	v_sub_f32_e32 v74, v82, v65
	v_sub_f32_e32 v66, v66, v65
	v_sub_f32_e32 v64, v246, v65
	v_exp_f32_e32 v92, v74
	v_sub_f32_e32 v74, v83, v65
	v_exp_f32_e32 v246, v66
	v_sub_f32_e32 v66, v67, v65
	v_exp_f32_e32 v93, v74
	v_sub_f32_e32 v74, v84, v65
	v_exp_f32_e32 v247, v66
	v_sub_f32_e32 v66, v68, v65
	v_exp_f32_e32 v94, v74
	v_sub_f32_e32 v74, v85, v65
	v_exp_f32_e32 v248, v66
	v_sub_f32_e32 v66, v69, v65
	v_exp_f32_e32 v95, v74
	v_sub_f32_e32 v74, v86, v65
	v_sub_f32_e32 v72, v72, v65
	v_exp_f32_e32 v249, v66
	v_sub_f32_e32 v66, v70, v65
	v_exp_f32_e32 v196, v74
	v_sub_f32_e32 v74, v87, v65
	v_exp_f32_e32 v198, v72
	v_sub_f32_e32 v72, v73, v65
	v_exp_f32_e32 v250, v66
	v_sub_f32_e32 v66, v71, v65
	v_exp_f32_e32 v64, v64
	v_exp_f32_e32 v197, v74
	v_exp_f32_e32 v199, v72
	v_exp_f32_e32 v251, v66
	v_cvt_pk_bf16_f32 v66, v90, v91
	v_cvt_pk_bf16_f32 v67, v92, v93
	v_cvt_pk_bf16_f32 v68, v94, v95
	v_cvt_pk_bf16_f32 v69, v196, v197
	v_cvt_pk_bf16_f32 v70, v198, v199
	v_cvt_pk_bf16_f32 v71, v246, v247
	v_cvt_pk_bf16_f32 v72, v248, v249
	v_cvt_pk_bf16_f32 v73, v250, v251
	ds_read_b64_tr_b16 v[74:75], v237
	ds_read_b64_tr_b16 v[76:77], v237 offset:2560
	v_pk_mul_f32 v[62:63], v[62:63], v[64:65] op_sel_hi:[1,0]
	v_pk_mul_f32 v[60:61], v[60:61], v[64:65] op_sel_hi:[1,0]
	v_pk_mul_f32 v[58:59], v[58:59], v[64:65] op_sel_hi:[1,0]
	v_pk_mul_f32 v[56:57], v[56:57], v[64:65] op_sel_hi:[1,0]
	v_pk_mul_f32 v[54:55], v[54:55], v[64:65] op_sel_hi:[1,0]
	v_pk_mul_f32 v[52:53], v[52:53], v[64:65] op_sel_hi:[1,0]
	v_pk_mul_f32 v[50:51], v[50:51], v[64:65] op_sel_hi:[1,0]
	v_pk_mul_f32 v[48:49], v[48:49], v[64:65] op_sel_hi:[1,0]
	ds_read_b64_tr_b16 v[78:79], v237 offset:64
	ds_read_b64_tr_b16 v[82:83], v237 offset:128
	ds_read_b64_tr_b16 v[86:87], v237 offset:192
	ds_read_b64_tr_b16 v[80:81], v237 offset:2624
	ds_read_b64_tr_b16 v[84:85], v237 offset:2688
	ds_read_b64_tr_b16 v[88:89], v237 offset:2752
	s_waitcnt lgkmcnt(0)
	v_mfma_f32_32x32x16_bf16 v[48:63], v[74:77], v[66:69], v[48:63]
	ds_read_b64_tr_b16 v[76:77], v237 offset:7680
	v_mul_f32_e64 v46, v46, v64
	v_mul_f32_e64 v47, v47, v64
	v_mul_f32_e64 v44, v44, v64
	v_mul_f32_e64 v45, v45, v64
	v_pk_mul_f32 v[42:43], v[42:43], v[64:65] op_sel_hi:[1,0]
	v_pk_mul_f32 v[40:41], v[40:41], v[64:65] op_sel_hi:[1,0]
	v_pk_mul_f32 v[38:39], v[38:39], v[64:65] op_sel_hi:[1,0]
	v_pk_mul_f32 v[36:37], v[36:37], v[64:65] op_sel_hi:[1,0]
	v_pk_mul_f32 v[34:35], v[34:35], v[64:65] op_sel_hi:[1,0]
	v_pk_mul_f32 v[32:33], v[32:33], v[64:65] op_sel_hi:[1,0]
	v_pk_mul_f32 v[30:31], v[30:31], v[64:65] op_sel_hi:[1,0]
	v_pk_mul_f32 v[28:29], v[28:29], v[64:65] op_sel_hi:[1,0]
	v_mfma_f32_32x32x16_bf16 v[32:47], v[78:81], v[66:69], v[32:47]
	v_mul_f32_e64 v26, v26, v64
	v_mul_f32_e64 v27, v27, v64
	v_mul_f32_e64 v24, v24, v64
	v_mul_f32_e64 v25, v25, v64
	v_mul_f32_e64 v22, v22, v64
	v_mul_f32_e64 v23, v23, v64
	v_pk_mul_f32 v[20:21], v[20:21], v[64:65] op_sel_hi:[1,0]
	v_pk_mul_f32 v[18:19], v[18:19], v[64:65] op_sel_hi:[1,0]
	v_pk_mul_f32 v[16:17], v[16:17], v[64:65] op_sel_hi:[1,0]
	v_pk_mul_f32 v[14:15], v[14:15], v[64:65] op_sel_hi:[1,0]
	v_pk_mul_f32 v[12:13], v[12:13], v[64:65] op_sel_hi:[1,0]
	v_pk_mul_f32 v[10:11], v[10:11], v[64:65] op_sel_hi:[1,0]
	v_pk_mul_f32 v[8:9], v[8:9], v[64:65] op_sel_hi:[1,0]
	v_pk_mul_f32 v[6:7], v[6:7], v[64:65] op_sel_hi:[1,0]
	v_pk_mul_f32 v[4:5], v[4:5], v[64:65] op_sel_hi:[1,0]
	v_pk_mul_f32 v[2:3], v[2:3], v[64:65] op_sel_hi:[1,0]
	v_pk_mul_f32 v[0:1], v[0:1], v[64:65] op_sel_hi:[1,0]
	v_mfma_f32_32x32x16_bf16 v[16:31], v[82:85], v[66:69], v[16:31]
	s_nop 0
	v_mfma_f32_32x32x16_bf16 v[0:15], v[86:89], v[66:69], v[0:15]
	ds_read_b64_tr_b16 v[74:75], v237 offset:5120
	ds_read_b64_tr_b16 v[66:67], v237 offset:5184
	ds_read_b64_tr_b16 v[78:79], v237 offset:5248
	ds_read_b64_tr_b16 v[82:83], v237 offset:5312
	ds_read_b64_tr_b16 v[68:69], v237 offset:7744
	ds_read_b64_tr_b16 v[80:81], v237 offset:7808
	ds_read_b64_tr_b16 v[84:85], v237 offset:7872
	s_waitcnt lgkmcnt(0)
	s_waitcnt lgkmcnt(0)
	v_mfma_f32_32x32x16_bf16 v[48:63], v[74:77], v[70:73], v[48:63]
	v_add_f32_e32 v74, 0, v90
	v_add_f32_e32 v74, v91, v74
	v_mfma_f32_32x32x16_bf16 v[32:47], v[66:69], v[70:73], v[32:47]
	v_add_f32_e32 v66, v92, v74
	v_add_f32_e32 v66, v93, v66
	v_add_f32_e32 v66, v94, v66
	v_add_f32_e32 v66, v95, v66
	v_add_f32_e32 v66, v196, v66
	v_add_f32_e32 v66, v197, v66
	v_add_f32_e32 v66, v198, v66
	v_mfma_f32_32x32x16_bf16 v[16:31], v[78:81], v[70:73], v[16:31]
	v_add_f32_e32 v66, v199, v66
	v_add_f32_e32 v66, v246, v66
	v_add_f32_e32 v66, v247, v66
	v_add_f32_e32 v66, v248, v66
	v_add_f32_e32 v66, v249, v66
	v_add_f32_e32 v66, v250, v66
	v_add_f32_e32 v66, v251, v66
	v_mfma_f32_32x32x16_bf16 v[0:15], v[82:85], v[70:73], v[0:15]
	v_fmac_f32_e32 v66, v245, v64
	s_cbranch_scc1 .LBB0_525
	v_mov_b32_e32 v245, v66
	v_mov_b32_e32 v246, v65
	s_branch .LBB0_521
